# deferred copies with 16-byte-per-lane LDS-DMA (8 requests per block instead of 32), otherwise as v61
# baseline (speedup 1.0000x reference)
; #define LAS __attribute__((address_space(3)))
; __device__ __forceinline__ void transpose_item(const float* W, int K, int N, bf16_t* WT, LAS float* scr, int item, int lane) {
;     const int nblk = (N + 31) / 32, kb = item / nblk, nb = item % nblk, k0 = 64 * kb, n0 = 32 * nb;
;     const int nn = n0 + (lane & 31); const bool ok = nn < N;
;     float v[32];
; #pragma unroll
;     for (int i = 0; i < 32; ++i) { const int kk = 2 * i + (lane >> 5); v[i] = ok ? W[(size_t)(k0 + kk) * N + nn] : 0.f; }
; #pragma unroll
;     for (int i = 0; i < 32; ++i) { const int kk = 2 * i + (lane >> 5); scr[kk * 33 + (lane & 31)] = v[i]; }
; __global__ void __launch_bounds__(512, 2) mega(Args a) {
;     ...
;         for (int it = it0; it < itN; it += its) {
;             int r = it;
;             if (r < 4 * I_IN) { const int l = r / I_IN; r -= l * I_IN; transpose_item(((const float*)ap->in[10]) + (size_t)l * DM * DIN, DM, DIN, WSP(bf16_t, WS_WIN) + (size_t)l * DINP * DM, scr, r, lane); }
;             else { r -= 4 * I_IN; const int l = r / I_OUT; r -= l * I_OUT; transpose_item(((const float*)ap->in[16]) + (size_t)l * DM * DM, DM, DM, WSP(bf16_t, WS_WOUT) + (size_t)l * DM * DM, scr, r, lane); }
.LBB0_150:
	s_ashr_i32 s5, s33, 6
	s_lshl_b32 s8, s13, 3
	s_add_i32 s8, s5, s8
	s_add_i32 s13, s8, s4
	s_cmp_ge_i32 s13, s14
	s_cbranch_scc1 .LBB0_221
	s_load_dwordx2 s[16:17], s[0:1], 0x50
	s_load_dwordx2 s[18:19], s[0:1], 0x80
	s_lshl_b32 s10, s5, 14
	s_mov_b32 s42, 0
	s_movk_i32 s43, 0x6060
	v_and_b32_e32 v18, 63, v162
	v_and_b32_e32 v19, 7, v18
	v_lshrrev_b32_e32 v20, 3, v18
	v_xor_b32_e32 v2, 0, v19
	v_lshlrev_b32_e32 v2, 4, v2
	v_xor_b32_e32 v3, 2, v19
	v_lshlrev_b32_e32 v3, 4, v3
	v_xor_b32_e32 v4, 4, v19
	v_lshlrev_b32_e32 v4, 4, v4
	v_xor_b32_e32 v5, 6, v19
	v_lshlrev_b32_e32 v5, 4, v5
	v_mov_b32_e32 v0, v20
	v_and_b32_e32 v19, 7, v18
	v_lshrrev_b32_e32 v20, 3, v18
	v_and_b32_e32 v21, 3, v19
	v_lshlrev_b32_e32 v22, 10, v19
	v_lshl_add_u32 v22, s5, 14, v22
	v_xor_b32_e32 v23, 0, v21
	v_lshl_add_u32 v23, v23, 3, v20
	v_lshl_add_u32 v8, v23, 2, v22
	v_xor_b32_e32 v23, 1, v21
	v_lshl_add_u32 v23, v23, 3, v20
	v_lshl_add_u32 v9, v23, 2, v22
	v_xor_b32_e32 v23, 2, v21
	v_lshl_add_u32 v23, v23, 3, v20
	v_lshl_add_u32 v10, v23, 2, v22
	v_xor_b32_e32 v23, 3, v21
	v_lshl_add_u32 v23, v23, 3, v20
	v_lshl_add_u32 v11, v23, 2, v22
	v_lshlrev_b32_e32 v23, 12, v20
	v_lshl_add_u32 v13, v19, 4, v23
	v_add_u32_e32 v14, 0x8000, v13
	v_add_u32_e32 v15, 0x10000, v13
	v_add_u32_e32 v16, 0x18000, v13
	s_mov_b32 s8, s13
	s_waitcnt vmcnt(0) lgkmcnt(0)
	v_readfirstlane_b32 s20, v128
	v_readfirstlane_b32 s21, v129
	s_mov_b32 s11, s8
	s_cmp_ge_u32 s11, 0x2020
	s_cselect_b32 s36, s43, s42
	s_add_u32 s11, s11, s36
	s_cmp_ge_u32 s11, 0x8080
	s_cbranch_scc1 .Lp0b_la_p0_out
	s_mul_hi_u32 s34, s11, 0x7f808
	s_mul_i32 s36, s34, 0x2020
	s_sub_u32 s11, s11, s36
	s_mul_hi_u32 s35, s11, 0xff0100
	s_mul_i32 s36, s35, 0x101
	s_sub_u32 s11, s11, s36
	s_mul_i32 s36, s34, 0x4020000
	s_mul_i32 s37, s35, 0x201000
	s_add_u32 s36, s36, s37
	s_lshl_b32 s37, s11, 7
	s_add_u32 s36, s36, s37
	s_add_u32 s22, s16, s36
	s_addc_u32 s23, s17, 0
	s_mov_b32 s26, 0x8040
	s_mov_b32 s27, 0x40200
	s_mov_b64 s[28:29], -1
	s_mov_b64 s[30:31], -1
	s_cmp_eq_u32 s11, 0x100
	s_cbranch_scc0 .Lp0b_la_p0_done
	s_mov_b32 s28, 0x0f0f0f0f
	s_mov_b32 s29, 0x0f0f0f0f
	s_mov_b32 s30, 0xf0f0f0f0
	s_mov_b32 s31, 0xf0f0f0f0
	s_branch .Lp0b_la_p0_done
.Lp0b_la_p0_out:
	s_sub_u32 s11, s11, 0x8080
	s_lshr_b32 s34, s11, 11
	s_and_b32 s11, s11, 0x7ff
	s_lshr_b32 s35, s11, 6
	s_and_b32 s11, s11, 63
	s_lshl_b32 s36, s34, 24
	s_lshl_b32 s37, s35, 19
	s_add_u32 s36, s36, s37
	s_lshl_b32 s37, s11, 7
	s_add_u32 s36, s36, s37
	s_add_u32 s22, s18, s36
	s_addc_u32 s23, s19, 0
	s_mov_b32 s26, 0x2000
	s_mov_b32 s27, 0x10000
	s_mov_b64 s[28:29], -1
	s_mov_b64 s[30:31], -1
.Lp0b_la_p0_done:
	v_mad_u32_u24 v58, v0, s26, v2
	v_mad_u32_u24 v59, v0, s26, v3
	v_mad_u32_u24 v60, v0, s26, v4
	v_mad_u32_u24 v61, v0, s26, v5
	s_mov_b64 exec, s[28:29]
	s_mov_b32 m0, s10
	s_nop 0
	global_load_lds_dwordx4 v58, s[22:23]
	s_add_i32 m0, m0, 0x400
	s_add_u32 s22, s22, s27
	s_addc_u32 s23, s23, 0
	global_load_lds_dwordx4 v59, s[22:23]
	s_mov_b64 exec, s[30:31]
	s_add_i32 m0, m0, 0x400
	s_add_u32 s22, s22, s27
	s_addc_u32 s23, s23, 0
	global_load_lds_dwordx4 v60, s[22:23]
	s_add_i32 m0, m0, 0x400
	s_add_u32 s22, s22, s27
	s_addc_u32 s23, s23, 0
	global_load_lds_dwordx4 v61, s[22:23]
	s_mov_b64 exec, s[28:29]
	s_add_i32 m0, m0, 0x400
	s_add_u32 s22, s22, s27
	s_addc_u32 s23, s23, 0
	global_load_lds_dwordx4 v58, s[22:23]
	s_add_i32 m0, m0, 0x400
	s_add_u32 s22, s22, s27
	s_addc_u32 s23, s23, 0
	global_load_lds_dwordx4 v59, s[22:23]
	s_mov_b64 exec, s[30:31]
	s_add_i32 m0, m0, 0x400
	s_add_u32 s22, s22, s27
	s_addc_u32 s23, s23, 0
	global_load_lds_dwordx4 v60, s[22:23]
	s_add_i32 m0, m0, 0x400
	s_add_u32 s22, s22, s27
	s_addc_u32 s23, s23, 0
	global_load_lds_dwordx4 v61, s[22:23]
	s_mov_b64 exec, -1
	s_add_i32 s9, s8, s15
	s_cmp_lt_i32 s9, s14
	s_cbranch_scc0 .Lp0b_nopf1
	s_mov_b32 s11, s9
	s_cmp_ge_u32 s11, 0x2020
	s_cselect_b32 s36, s43, s42
	s_add_u32 s11, s11, s36
	s_cmp_ge_u32 s11, 0x8080
	s_cbranch_scc1 .Lp0b_la_p1_out
	s_mul_hi_u32 s34, s11, 0x7f808
	s_mul_i32 s36, s34, 0x2020
	s_sub_u32 s11, s11, s36
	s_mul_hi_u32 s35, s11, 0xff0100
	s_mul_i32 s36, s35, 0x101
	s_sub_u32 s11, s11, s36
	s_mul_i32 s36, s34, 0x4020000
	s_mul_i32 s37, s35, 0x201000
	s_add_u32 s36, s36, s37
	s_lshl_b32 s37, s11, 7
	s_add_u32 s36, s36, s37
	s_add_u32 s22, s16, s36
	s_addc_u32 s23, s17, 0
	s_mov_b32 s26, 0x8040
	s_mov_b32 s27, 0x40200
	s_mov_b64 s[28:29], -1
	s_mov_b64 s[30:31], -1
	s_cmp_eq_u32 s11, 0x100
	s_cbranch_scc0 .Lp0b_la_p1_done
	s_mov_b32 s28, 0x0f0f0f0f
	s_mov_b32 s29, 0x0f0f0f0f
	s_mov_b32 s30, 0xf0f0f0f0
	s_mov_b32 s31, 0xf0f0f0f0
	s_branch .Lp0b_la_p1_done

; #define LAS __attribute__((address_space(3)))
; __device__ __forceinline__ void transpose_item(const float* W, int K, int N, bf16_t* WT, LAS float* scr, int item, int lane) {
;     const int nblk = (N + 31) / 32, kb = item / nblk, nb = item % nblk, k0 = 64 * kb, n0 = 32 * nb;
;     const int nn = n0 + (lane & 31); const bool ok = nn < N;
;     float v[32];
; #pragma unroll
;     for (int i = 0; i < 32; ++i) { const int kk = 2 * i + (lane >> 5); v[i] = ok ? W[(size_t)(k0 + kk) * N + nn] : 0.f; }
; #pragma unroll
;     for (int i = 0; i < 32; ++i) { const int kk = 2 * i + (lane >> 5); scr[kk * 33 + (lane & 31)] = v[i]; }
.Lp0b_la_p1_done:
	v_mad_u32_u24 v58, v0, s26, v2
	v_mad_u32_u24 v59, v0, s26, v3
	v_mad_u32_u24 v60, v0, s26, v4
	v_mad_u32_u24 v61, v0, s26, v5
	s_mov_b64 exec, s[28:29]
	s_xor_b32 m0, s10, 0x2000
	s_nop 0
	global_load_lds_dwordx4 v58, s[22:23]
	s_add_i32 m0, m0, 0x400
	s_add_u32 s22, s22, s27
	s_addc_u32 s23, s23, 0
	global_load_lds_dwordx4 v59, s[22:23]
	s_mov_b64 exec, s[30:31]
	s_add_i32 m0, m0, 0x400
	s_add_u32 s22, s22, s27
	s_addc_u32 s23, s23, 0
	global_load_lds_dwordx4 v60, s[22:23]
	s_add_i32 m0, m0, 0x400
	s_add_u32 s22, s22, s27
	s_addc_u32 s23, s23, 0
	global_load_lds_dwordx4 v61, s[22:23]
	s_mov_b64 exec, s[28:29]
	s_add_i32 m0, m0, 0x400
	s_add_u32 s22, s22, s27
	s_addc_u32 s23, s23, 0
	global_load_lds_dwordx4 v58, s[22:23]
	s_add_i32 m0, m0, 0x400
	s_add_u32 s22, s22, s27
	s_addc_u32 s23, s23, 0
	global_load_lds_dwordx4 v59, s[22:23]
	s_mov_b64 exec, s[30:31]
	s_add_i32 m0, m0, 0x400
	s_add_u32 s22, s22, s27
	s_addc_u32 s23, s23, 0
	global_load_lds_dwordx4 v60, s[22:23]
	s_add_i32 m0, m0, 0x400
	s_add_u32 s22, s22, s27
	s_addc_u32 s23, s23, 0
	global_load_lds_dwordx4 v61, s[22:23]
	s_mov_b64 exec, -1

; #define LAS __attribute__((address_space(3)))
; __device__ __forceinline__ unsigned pk2(float lo, float hi) { return pg8::cvt_pk_bf16(lo, hi); }
; #define LDS_WAIT() asm volatile("s_waitcnt lgkmcnt(0)" ::: "memory")
; __device__ __forceinline__ void transpose_item(const float* W, int K, int N, bf16_t* WT, LAS float* scr, int item, int lane) {
;     const int nblk = (N + 31) / 32, kb = item / nblk, nb = item % nblk, k0 = 64 * kb, n0 = 32 * nb;
;     const int nn = n0 + (lane & 31); const bool ok = nn < N;
;     float v[32];
; #pragma unroll
;     for (int i = 0; i < 32; ++i) { const int kk = 2 * i + (lane >> 5); v[i] = ok ? W[(size_t)(k0 + kk) * N + nn] : 0.f; }
; #pragma unroll
;     for (int i = 0; i < 32; ++i) { const int kk = 2 * i + (lane >> 5); scr[kk * 33 + (lane & 31)] = v[i]; }
;     LDS_WAIT(); asm volatile("" ::: "memory");
;     const int c = lane & 7;
; #pragma unroll
;     for (int j = 0; j < 4; ++j) { const int n = (lane >> 3) + 8 * j; const LAS float* s = scr + (8 * c) * 33 + n;
;         u32x4 o; o.x = pk2(s[0 * 33], s[1 * 33]); o.y = pk2(s[2 * 33], s[3 * 33]); o.z = pk2(s[4 * 33], s[5 * 33]); o.w = pk2(s[6 * 33], s[7 * 33]);
;         *(u32x4*)(WT + (size_t)(n0 + n) * K + k0 + 8 * c) = o; }
.Lp0b_w32:
	s_waitcnt vmcnt(8)
.Lp0b_wd:
	ds_read2_b32 v[18:19], v8 offset0:0 offset1:32
	ds_read2_b32 v[20:21], v8 offset0:64 offset1:96
	ds_read2_b32 v[22:23], v8 offset0:128 offset1:160
	ds_read2_b32 v[24:25], v8 offset0:192 offset1:224
	ds_read2_b32 v[26:27], v9 offset0:0 offset1:32
	ds_read2_b32 v[28:29], v9 offset0:64 offset1:96
	ds_read2_b32 v[30:31], v9 offset0:128 offset1:160
	ds_read2_b32 v[32:33], v9 offset0:192 offset1:224
	ds_read2_b32 v[34:35], v10 offset0:0 offset1:32
	ds_read2_b32 v[36:37], v10 offset0:64 offset1:96
	ds_read2_b32 v[38:39], v10 offset0:128 offset1:160
	ds_read2_b32 v[40:41], v10 offset0:192 offset1:224
	ds_read2_b32 v[42:43], v11 offset0:0 offset1:32
	ds_read2_b32 v[44:45], v11 offset0:64 offset1:96
	ds_read2_b32 v[46:47], v11 offset0:128 offset1:160
	ds_read2_b32 v[48:49], v11 offset0:192 offset1:224
	s_waitcnt lgkmcnt(12)
	v_cvt_pk_bf16_f32 v50, v18, v19
	v_cvt_pk_bf16_f32 v51, v20, v21
	v_cvt_pk_bf16_f32 v52, v22, v23
	v_cvt_pk_bf16_f32 v53, v24, v25
	global_store_dwordx4 v13, v[50:53], s[24:25]
	s_waitcnt lgkmcnt(8)
	v_cvt_pk_bf16_f32 v54, v26, v27
	v_cvt_pk_bf16_f32 v55, v28, v29
	v_cvt_pk_bf16_f32 v56, v30, v31
	v_cvt_pk_bf16_f32 v57, v32, v33
	global_store_dwordx4 v14, v[54:57], s[24:25]
	s_waitcnt lgkmcnt(4)
	v_cvt_pk_bf16_f32 v50, v34, v35
	v_cvt_pk_bf16_f32 v51, v36, v37
	v_cvt_pk_bf16_f32 v52, v38, v39
	v_cvt_pk_bf16_f32 v53, v40, v41
	v_cndmask_b32_e64 v50, v50, 0, s[40:41]
	v_cndmask_b32_e64 v51, v51, 0, s[40:41]
	v_cndmask_b32_e64 v52, v52, 0, s[40:41]
	v_cndmask_b32_e64 v53, v53, 0, s[40:41]
	global_store_dwordx4 v15, v[50:53], s[24:25]
	s_waitcnt lgkmcnt(0)
	v_cvt_pk_bf16_f32 v54, v42, v43
	v_cvt_pk_bf16_f32 v55, v44, v45
	v_cvt_pk_bf16_f32 v56, v46, v47
	v_cvt_pk_bf16_f32 v57, v48, v49
	v_cndmask_b32_e64 v54, v54, 0, s[40:41]
	v_cndmask_b32_e64 v55, v55, 0, s[40:41]
	v_cndmask_b32_e64 v56, v56, 0, s[40:41]
	v_cndmask_b32_e64 v57, v57, 0, s[40:41]
	global_store_dwordx4 v16, v[54:57], s[24:25]
	s_cmp_lt_i32 s9, s14
	s_cbranch_scc0 .Lp0b_nopf
	s_mov_b32 s11, s9
	s_cmp_ge_u32 s11, 0x2020
	s_cselect_b32 s36, s43, s42
	s_add_u32 s11, s11, s36
	s_cmp_ge_u32 s11, 0x8080
	s_cbranch_scc1 .Lp0b_la_lp_out
	s_mul_hi_u32 s34, s11, 0x7f808
	s_mul_i32 s36, s34, 0x2020
	s_sub_u32 s11, s11, s36
	s_mul_hi_u32 s35, s11, 0xff0100
	s_mul_i32 s36, s35, 0x101
	s_sub_u32 s11, s11, s36
	s_mul_i32 s36, s34, 0x4020000
	s_mul_i32 s37, s35, 0x201000
	s_add_u32 s36, s36, s37
	s_lshl_b32 s37, s11, 7
	s_add_u32 s36, s36, s37
	s_add_u32 s22, s16, s36
	s_addc_u32 s23, s17, 0
	s_mov_b32 s26, 0x8040
	s_mov_b32 s27, 0x40200
	s_mov_b64 s[28:29], -1
	s_mov_b64 s[30:31], -1
	s_cmp_eq_u32 s11, 0x100
	s_cbranch_scc0 .Lp0b_la_lp_done
	s_mov_b32 s28, 0x0f0f0f0f
	s_mov_b32 s29, 0x0f0f0f0f
	s_mov_b32 s30, 0xf0f0f0f0
	s_mov_b32 s31, 0xf0f0f0f0
	s_branch .Lp0b_la_lp_done

; #define LAS __attribute__((address_space(3)))
; __device__ __forceinline__ void transpose_item(const float* W, int K, int N, bf16_t* WT, LAS float* scr, int item, int lane) {
;     const int nblk = (N + 31) / 32, kb = item / nblk, nb = item % nblk, k0 = 64 * kb, n0 = 32 * nb;
;     const int nn = n0 + (lane & 31); const bool ok = nn < N;
;     float v[32];
; #pragma unroll
;     for (int i = 0; i < 32; ++i) { const int kk = 2 * i + (lane >> 5); v[i] = ok ? W[(size_t)(k0 + kk) * N + nn] : 0.f; }
; #pragma unroll
;     for (int i = 0; i < 32; ++i) { const int kk = 2 * i + (lane >> 5); scr[kk * 33 + (lane & 31)] = v[i]; }
.Lp0b_la_lp_done:
	v_mad_u32_u24 v58, v0, s26, v2
	v_mad_u32_u24 v59, v0, s26, v3
	v_mad_u32_u24 v60, v0, s26, v4
	v_mad_u32_u24 v61, v0, s26, v5
	s_mov_b64 exec, s[28:29]
	s_mov_b32 m0, s10
	s_nop 0
	global_load_lds_dwordx4 v58, s[22:23]
	s_add_i32 m0, m0, 0x400
	s_add_u32 s22, s22, s27
	s_addc_u32 s23, s23, 0
	global_load_lds_dwordx4 v59, s[22:23]
	s_mov_b64 exec, s[30:31]
	s_add_i32 m0, m0, 0x400
	s_add_u32 s22, s22, s27
	s_addc_u32 s23, s23, 0
	global_load_lds_dwordx4 v60, s[22:23]
	s_add_i32 m0, m0, 0x400
	s_add_u32 s22, s22, s27
	s_addc_u32 s23, s23, 0
	global_load_lds_dwordx4 v61, s[22:23]
	s_mov_b64 exec, s[28:29]
	s_add_i32 m0, m0, 0x400
	s_add_u32 s22, s22, s27
	s_addc_u32 s23, s23, 0
	global_load_lds_dwordx4 v58, s[22:23]
	s_add_i32 m0, m0, 0x400
	s_add_u32 s22, s22, s27
	s_addc_u32 s23, s23, 0
	global_load_lds_dwordx4 v59, s[22:23]
	s_mov_b64 exec, s[30:31]
	s_add_i32 m0, m0, 0x400
	s_add_u32 s22, s22, s27
	s_addc_u32 s23, s23, 0
	global_load_lds_dwordx4 v60, s[22:23]
	s_add_i32 m0, m0, 0x400
	s_add_u32 s22, s22, s27
	s_addc_u32 s23, s23, 0
	global_load_lds_dwordx4 v61, s[22:23]
	s_mov_b64 exec, -1

; #define LAS __attribute__((address_space(3)))
; __device__ __forceinline__ void transpose_item(const float* W, int K, int N, bf16_t* WT, LAS float* scr, int item, int lane) {
;     const int nblk = (N + 31) / 32, kb = item / nblk, nb = item % nblk, k0 = 64 * kb, n0 = 32 * nb;
;     const int nn = n0 + (lane & 31); const bool ok = nn < N;
;     float v[32];
; #pragma unroll
;     for (int i = 0; i < 32; ++i) { const int kk = 2 * i + (lane >> 5); v[i] = ok ? W[(size_t)(k0 + kk) * N + nn] : 0.f; }
; #pragma unroll
;     for (int i = 0; i < 32; ++i) { const int kk = 2 * i + (lane >> 5); scr[kk * 33 + (lane & 31)] = v[i]; }
; __global__ void __launch_bounds__(512, 2) mega(Args a) {
;     ...
;         for (int it = it0; it < itN; it += its) {
;             int r = it;
;             if (r < 4 * I_IN) { const int l = r / I_IN; r -= l * I_IN; transpose_item(((const float*)ap->in[10]) + (size_t)l * DM * DIN, DM, DIN, WSP(bf16_t, WS_WIN) + (size_t)l * DINP * DM, scr, r, lane); }
;             else { r -= 4 * I_IN; const int l = r / I_OUT; r -= l * I_OUT; transpose_item(((const float*)ap->in[16]) + (size_t)l * DM * DM, DM, DM, WSP(bf16_t, WS_WOUT) + (size_t)l * DM * DM, scr, r, lane); }
.LBB0_513:
	s_or_b64 exec, exec, s[4:5]
	s_mov_b64 exec, -1
	s_waitcnt vmcnt(0) lgkmcnt(0)
	s_cmp_gt_u32 s92, 2
	s_cbranch_scc1 .Lp4t_skip
	s_load_dwordx2 s[22:23], s[0:1], 0x50
	s_load_dwordx2 s[24:25], s[0:1], 0x80
	s_load_dwordx2 s[26:27], s[0:1], 0x98
	s_lshr_b32 s38, s3, 6
	s_lshl_b32 s6, s38, 14
	v_mbcnt_lo_u32_b32 v24, -1, 0
	v_mbcnt_hi_u32_b32 v24, -1, v24
	v_and_b32_e32 v18, 63, v24
	v_and_b32_e32 v19, 7, v18
	v_lshrrev_b32_e32 v20, 3, v18
	v_xor_b32_e32 v2, 0, v19
	v_lshlrev_b32_e32 v2, 4, v2
	v_xor_b32_e32 v3, 2, v19
	v_lshlrev_b32_e32 v3, 4, v3
	v_xor_b32_e32 v4, 4, v19
	v_lshlrev_b32_e32 v4, 4, v4
	v_xor_b32_e32 v5, 6, v19
	v_lshlrev_b32_e32 v5, 4, v5
	v_mov_b32_e32 v0, v20
	v_and_b32_e32 v19, 7, v18
	v_lshrrev_b32_e32 v20, 3, v18
	v_and_b32_e32 v21, 3, v19
	v_lshlrev_b32_e32 v22, 10, v19
	v_lshl_add_u32 v22, s38, 14, v22
	v_xor_b32_e32 v23, 0, v21
	v_lshl_add_u32 v23, v23, 3, v20
	v_lshl_add_u32 v62, v23, 2, v22
	v_xor_b32_e32 v23, 1, v21
	v_lshl_add_u32 v23, v23, 3, v20
	v_lshl_add_u32 v63, v23, 2, v22
	v_xor_b32_e32 v23, 2, v21
	v_lshl_add_u32 v23, v23, 3, v20
	v_lshl_add_u32 v64, v23, 2, v22
	v_xor_b32_e32 v23, 3, v21
	v_lshl_add_u32 v23, v23, 3, v20
	v_lshl_add_u32 v65, v23, 2, v22
	v_lshlrev_b32_e32 v23, 12, v20
	v_lshl_add_u32 v13, v19, 4, v23
	v_add_u32_e32 v14, 0x8000, v13
	v_add_u32_e32 v15, 0x10000, v13
	v_add_u32_e32 v16, 0x18000, v13
	s_sub_u32 s4, s2, 64
	s_lshl_b32 s4, s4, 3
	s_add_u32 s4, s4, s38
	s_movk_i32 s16, 0x2820
	s_movk_i32 s18, 0x600
	s_add_u32 s70, s92, 1
	s_mul_i32 s98, s70, 0x2020
	s_lshl_b32 s99, s70, 11
	s_addk_i32 s99, 0x6060
	s_waitcnt lgkmcnt(0)
	s_mov_b32 s7, s4
	s_cmp_ge_u32 s7, 0x2020
	s_cselect_b32 s70, s99, s98
	s_add_u32 s7, s7, s70
	s_cmp_ge_u32 s7, 0x8080
	s_cbranch_scc1 .Lp4t_la_p0_out
	s_mul_hi_u32 s38, s7, 0x7f808
	s_mul_i32 s70, s38, 0x2020
	s_sub_u32 s7, s7, s70
	s_mul_hi_u32 s55, s7, 0xff0100
	s_mul_i32 s70, s55, 0x101
	s_sub_u32 s7, s7, s70
	s_mul_i32 s70, s38, 0x4020000
	s_mul_i32 s71, s55, 0x201000
	s_add_u32 s70, s70, s71
	s_lshl_b32 s71, s7, 7
	s_add_u32 s70, s70, s71
	s_add_u32 s28, s22, s70
	s_addc_u32 s29, s23, 0
	s_mov_b32 s19, 0x8040
	s_mov_b32 s32, 0x40200
	s_mov_b64 s[34:35], -1
	s_mov_b64 s[36:37], -1
	s_cmp_eq_u32 s7, 0x100
	s_cbranch_scc0 .Lp4t_la_p0_done
	s_mov_b32 s34, 0x0f0f0f0f
	s_mov_b32 s35, 0x0f0f0f0f
	s_mov_b32 s36, 0xf0f0f0f0
	s_mov_b32 s37, 0xf0f0f0f0
	s_branch .Lp4t_la_p0_done
.Lp4t_la_p0_out:
	s_sub_u32 s7, s7, 0x8080
	s_lshr_b32 s38, s7, 11
	s_and_b32 s7, s7, 0x7ff
	s_lshr_b32 s55, s7, 6
	s_and_b32 s7, s7, 63
	s_lshl_b32 s70, s38, 24
	s_lshl_b32 s71, s55, 19
	s_add_u32 s70, s70, s71
	s_lshl_b32 s71, s7, 7
	s_add_u32 s70, s70, s71
	s_add_u32 s28, s24, s70
	s_addc_u32 s29, s25, 0
	s_mov_b32 s19, 0x2000
	s_mov_b32 s32, 0x10000
	s_mov_b64 s[34:35], -1
	s_mov_b64 s[36:37], -1
.Lp4t_la_p0_done:
	v_mad_u32_u24 v58, v0, s19, v2
	v_mad_u32_u24 v59, v0, s19, v3
	v_mad_u32_u24 v60, v0, s19, v4
	v_mad_u32_u24 v61, v0, s19, v5
	s_mov_b64 exec, s[34:35]
	s_mov_b32 m0, s6
	s_nop 0
	global_load_lds_dwordx4 v58, s[28:29]
	s_add_i32 m0, m0, 0x400
	s_add_u32 s28, s28, s32
	s_addc_u32 s29, s29, 0
	global_load_lds_dwordx4 v59, s[28:29]
	s_mov_b64 exec, s[36:37]
	s_add_i32 m0, m0, 0x400
	s_add_u32 s28, s28, s32
	s_addc_u32 s29, s29, 0
	global_load_lds_dwordx4 v60, s[28:29]
	s_add_i32 m0, m0, 0x400
	s_add_u32 s28, s28, s32
	s_addc_u32 s29, s29, 0
	global_load_lds_dwordx4 v61, s[28:29]
	s_mov_b64 exec, s[34:35]
	s_add_i32 m0, m0, 0x400
	s_add_u32 s28, s28, s32
	s_addc_u32 s29, s29, 0
	global_load_lds_dwordx4 v58, s[28:29]
	s_add_i32 m0, m0, 0x400
	s_add_u32 s28, s28, s32
	s_addc_u32 s29, s29, 0
	global_load_lds_dwordx4 v59, s[28:29]
	s_mov_b64 exec, s[36:37]
	s_add_i32 m0, m0, 0x400
	s_add_u32 s28, s28, s32
	s_addc_u32 s29, s29, 0
	global_load_lds_dwordx4 v60, s[28:29]
	s_add_i32 m0, m0, 0x400
	s_add_u32 s28, s28, s32
	s_addc_u32 s29, s29, 0
	global_load_lds_dwordx4 v61, s[28:29]
	s_mov_b64 exec, -1
	s_add_i32 s5, s4, s18
	s_cmp_lt_i32 s5, s16
	s_cbranch_scc0 .Lp4t_nopf1
	s_mov_b32 s7, s5
	s_cmp_ge_u32 s7, 0x2020
	s_cselect_b32 s70, s99, s98
	s_add_u32 s7, s7, s70
	s_cmp_ge_u32 s7, 0x8080
	s_cbranch_scc1 .Lp4t_la_p1_out
	s_mul_hi_u32 s38, s7, 0x7f808
	s_mul_i32 s70, s38, 0x2020
	s_sub_u32 s7, s7, s70
	s_mul_hi_u32 s55, s7, 0xff0100
	s_mul_i32 s70, s55, 0x101
	s_sub_u32 s7, s7, s70
	s_mul_i32 s70, s38, 0x4020000
	s_mul_i32 s71, s55, 0x201000
	s_add_u32 s70, s70, s71
	s_lshl_b32 s71, s7, 7
	s_add_u32 s70, s70, s71
	s_add_u32 s28, s22, s70
	s_addc_u32 s29, s23, 0
	s_mov_b32 s19, 0x8040
	s_mov_b32 s32, 0x40200
	s_mov_b64 s[34:35], -1
	s_mov_b64 s[36:37], -1
	s_cmp_eq_u32 s7, 0x100
	s_cbranch_scc0 .Lp4t_la_p1_done
	s_mov_b32 s34, 0x0f0f0f0f
	s_mov_b32 s35, 0x0f0f0f0f
	s_mov_b32 s36, 0xf0f0f0f0
	s_mov_b32 s37, 0xf0f0f0f0
	s_branch .Lp4t_la_p1_done

; #define LAS __attribute__((address_space(3)))
; __device__ __forceinline__ void transpose_item(const float* W, int K, int N, bf16_t* WT, LAS float* scr, int item, int lane) {
;     const int nblk = (N + 31) / 32, kb = item / nblk, nb = item % nblk, k0 = 64 * kb, n0 = 32 * nb;
;     const int nn = n0 + (lane & 31); const bool ok = nn < N;
;     float v[32];
; #pragma unroll
;     for (int i = 0; i < 32; ++i) { const int kk = 2 * i + (lane >> 5); v[i] = ok ? W[(size_t)(k0 + kk) * N + nn] : 0.f; }
; #pragma unroll
;     for (int i = 0; i < 32; ++i) { const int kk = 2 * i + (lane >> 5); scr[kk * 33 + (lane & 31)] = v[i]; }
.Lp4t_la_p1_done:
	v_mad_u32_u24 v58, v0, s19, v2
	v_mad_u32_u24 v59, v0, s19, v3
	v_mad_u32_u24 v60, v0, s19, v4
	v_mad_u32_u24 v61, v0, s19, v5
	s_mov_b64 exec, s[34:35]
	s_xor_b32 m0, s6, 0x2000
	s_nop 0
	global_load_lds_dwordx4 v58, s[28:29]
	s_add_i32 m0, m0, 0x400
	s_add_u32 s28, s28, s32
	s_addc_u32 s29, s29, 0
	global_load_lds_dwordx4 v59, s[28:29]
	s_mov_b64 exec, s[36:37]
	s_add_i32 m0, m0, 0x400
	s_add_u32 s28, s28, s32
	s_addc_u32 s29, s29, 0
	global_load_lds_dwordx4 v60, s[28:29]
	s_add_i32 m0, m0, 0x400
	s_add_u32 s28, s28, s32
	s_addc_u32 s29, s29, 0
	global_load_lds_dwordx4 v61, s[28:29]
	s_mov_b64 exec, s[34:35]
	s_add_i32 m0, m0, 0x400
	s_add_u32 s28, s28, s32
	s_addc_u32 s29, s29, 0
	global_load_lds_dwordx4 v58, s[28:29]
	s_add_i32 m0, m0, 0x400
	s_add_u32 s28, s28, s32
	s_addc_u32 s29, s29, 0
	global_load_lds_dwordx4 v59, s[28:29]
	s_mov_b64 exec, s[36:37]
	s_add_i32 m0, m0, 0x400
	s_add_u32 s28, s28, s32
	s_addc_u32 s29, s29, 0
	global_load_lds_dwordx4 v60, s[28:29]
	s_add_i32 m0, m0, 0x400
	s_add_u32 s28, s28, s32
	s_addc_u32 s29, s29, 0
	global_load_lds_dwordx4 v61, s[28:29]
	s_mov_b64 exec, -1

; #define LAS __attribute__((address_space(3)))
; __device__ __forceinline__ unsigned pk2(float lo, float hi) { return pg8::cvt_pk_bf16(lo, hi); }
; #define LDS_WAIT() asm volatile("s_waitcnt lgkmcnt(0)" ::: "memory")
; __device__ __forceinline__ void transpose_item(const float* W, int K, int N, bf16_t* WT, LAS float* scr, int item, int lane) {
;     const int nblk = (N + 31) / 32, kb = item / nblk, nb = item % nblk, k0 = 64 * kb, n0 = 32 * nb;
;     const int nn = n0 + (lane & 31); const bool ok = nn < N;
;     float v[32];
; #pragma unroll
;     for (int i = 0; i < 32; ++i) { const int kk = 2 * i + (lane >> 5); v[i] = ok ? W[(size_t)(k0 + kk) * N + nn] : 0.f; }
; #pragma unroll
;     for (int i = 0; i < 32; ++i) { const int kk = 2 * i + (lane >> 5); scr[kk * 33 + (lane & 31)] = v[i]; }
;     LDS_WAIT(); asm volatile("" ::: "memory");
;     const int c = lane & 7;
; #pragma unroll
;     for (int j = 0; j < 4; ++j) { const int n = (lane >> 3) + 8 * j; const LAS float* s = scr + (8 * c) * 33 + n;
;         u32x4 o; o.x = pk2(s[0 * 33], s[1 * 33]); o.y = pk2(s[2 * 33], s[3 * 33]); o.z = pk2(s[4 * 33], s[5 * 33]); o.w = pk2(s[6 * 33], s[7 * 33]);
;         *(u32x4*)(WT + (size_t)(n0 + n) * K + k0 + 8 * c) = o; }
.Lp4t_wd:
	ds_read2_b32 v[18:19], v62 offset0:0 offset1:32
	ds_read2_b32 v[20:21], v62 offset0:64 offset1:96
	ds_read2_b32 v[22:23], v62 offset0:128 offset1:160
	ds_read2_b32 v[24:25], v62 offset0:192 offset1:224
	ds_read2_b32 v[26:27], v63 offset0:0 offset1:32
	ds_read2_b32 v[28:29], v63 offset0:64 offset1:96
	ds_read2_b32 v[30:31], v63 offset0:128 offset1:160
	ds_read2_b32 v[32:33], v63 offset0:192 offset1:224
	ds_read2_b32 v[34:35], v64 offset0:0 offset1:32
	ds_read2_b32 v[36:37], v64 offset0:64 offset1:96
	ds_read2_b32 v[38:39], v64 offset0:128 offset1:160
	ds_read2_b32 v[40:41], v64 offset0:192 offset1:224
	ds_read2_b32 v[42:43], v65 offset0:0 offset1:32
	ds_read2_b32 v[44:45], v65 offset0:64 offset1:96
	ds_read2_b32 v[46:47], v65 offset0:128 offset1:160
	ds_read2_b32 v[48:49], v65 offset0:192 offset1:224
	s_waitcnt lgkmcnt(12)
	v_cvt_pk_bf16_f32 v50, v18, v19
	v_cvt_pk_bf16_f32 v51, v20, v21
	v_cvt_pk_bf16_f32 v52, v22, v23
	v_cvt_pk_bf16_f32 v53, v24, v25
	global_store_dwordx4 v13, v[50:53], s[30:31]
	s_waitcnt lgkmcnt(8)
	v_cvt_pk_bf16_f32 v54, v26, v27
	v_cvt_pk_bf16_f32 v55, v28, v29
	v_cvt_pk_bf16_f32 v56, v30, v31
	v_cvt_pk_bf16_f32 v57, v32, v33
	global_store_dwordx4 v14, v[54:57], s[30:31]
	s_waitcnt lgkmcnt(4)
	v_cvt_pk_bf16_f32 v50, v34, v35
	v_cvt_pk_bf16_f32 v51, v36, v37
	v_cvt_pk_bf16_f32 v52, v38, v39
	v_cvt_pk_bf16_f32 v53, v40, v41
	v_cndmask_b32_e64 v50, v50, 0, s[48:49]
	v_cndmask_b32_e64 v51, v51, 0, s[48:49]
	v_cndmask_b32_e64 v52, v52, 0, s[48:49]
	v_cndmask_b32_e64 v53, v53, 0, s[48:49]
	global_store_dwordx4 v15, v[50:53], s[30:31]
	s_waitcnt lgkmcnt(0)
	v_cvt_pk_bf16_f32 v54, v42, v43
	v_cvt_pk_bf16_f32 v55, v44, v45
	v_cvt_pk_bf16_f32 v56, v46, v47
	v_cvt_pk_bf16_f32 v57, v48, v49
	v_cndmask_b32_e64 v54, v54, 0, s[48:49]
	v_cndmask_b32_e64 v55, v55, 0, s[48:49]
	v_cndmask_b32_e64 v56, v56, 0, s[48:49]
	v_cndmask_b32_e64 v57, v57, 0, s[48:49]
	global_store_dwordx4 v16, v[54:57], s[30:31]
	s_cmp_lt_i32 s5, s16
	s_cbranch_scc0 .Lp4t_nopf
	s_mov_b32 s7, s5
	s_cmp_ge_u32 s7, 0x2020
	s_cselect_b32 s70, s99, s98
	s_add_u32 s7, s7, s70
	s_cmp_ge_u32 s7, 0x8080
	s_cbranch_scc1 .Lp4t_la_lp_out
	s_mul_hi_u32 s38, s7, 0x7f808
	s_mul_i32 s70, s38, 0x2020
	s_sub_u32 s7, s7, s70
	s_mul_hi_u32 s55, s7, 0xff0100
	s_mul_i32 s70, s55, 0x101
	s_sub_u32 s7, s7, s70
	s_mul_i32 s70, s38, 0x4020000
	s_mul_i32 s71, s55, 0x201000
	s_add_u32 s70, s70, s71
	s_lshl_b32 s71, s7, 7
	s_add_u32 s70, s70, s71
	s_add_u32 s28, s22, s70
	s_addc_u32 s29, s23, 0
	s_mov_b32 s19, 0x8040
	s_mov_b32 s32, 0x40200
	s_mov_b64 s[34:35], -1
	s_mov_b64 s[36:37], -1
	s_cmp_eq_u32 s7, 0x100
	s_cbranch_scc0 .Lp4t_la_lp_done
	s_mov_b32 s34, 0x0f0f0f0f
	s_mov_b32 s35, 0x0f0f0f0f
	s_mov_b32 s36, 0xf0f0f0f0
	s_mov_b32 s37, 0xf0f0f0f0
	s_branch .Lp4t_la_lp_done

; #define LAS __attribute__((address_space(3)))
; __device__ __forceinline__ void transpose_item(const float* W, int K, int N, bf16_t* WT, LAS float* scr, int item, int lane) {
;     const int nblk = (N + 31) / 32, kb = item / nblk, nb = item % nblk, k0 = 64 * kb, n0 = 32 * nb;
;     const int nn = n0 + (lane & 31); const bool ok = nn < N;
;     float v[32];
; #pragma unroll
;     for (int i = 0; i < 32; ++i) { const int kk = 2 * i + (lane >> 5); v[i] = ok ? W[(size_t)(k0 + kk) * N + nn] : 0.f; }
; #pragma unroll
;     for (int i = 0; i < 32; ++i) { const int kk = 2 * i + (lane >> 5); scr[kk * 33 + (lane & 31)] = v[i]; }
.Lp4t_la_lp_done:
	v_mad_u32_u24 v58, v0, s19, v2
	v_mad_u32_u24 v59, v0, s19, v3
	v_mad_u32_u24 v60, v0, s19, v4
	v_mad_u32_u24 v61, v0, s19, v5
	s_mov_b64 exec, s[34:35]
	s_mov_b32 m0, s6
	s_nop 0
	global_load_lds_dwordx4 v58, s[28:29]
	s_add_i32 m0, m0, 0x400
	s_add_u32 s28, s28, s32
	s_addc_u32 s29, s29, 0
	global_load_lds_dwordx4 v59, s[28:29]
	s_mov_b64 exec, s[36:37]
	s_add_i32 m0, m0, 0x400
	s_add_u32 s28, s28, s32
	s_addc_u32 s29, s29, 0
	global_load_lds_dwordx4 v60, s[28:29]
	s_add_i32 m0, m0, 0x400
	s_add_u32 s28, s28, s32
	s_addc_u32 s29, s29, 0
	global_load_lds_dwordx4 v61, s[28:29]
	s_mov_b64 exec, s[34:35]
	s_add_i32 m0, m0, 0x400
	s_add_u32 s28, s28, s32
	s_addc_u32 s29, s29, 0
	global_load_lds_dwordx4 v58, s[28:29]
	s_add_i32 m0, m0, 0x400
	s_add_u32 s28, s28, s32
	s_addc_u32 s29, s29, 0
	global_load_lds_dwordx4 v59, s[28:29]
	s_mov_b64 exec, s[36:37]
	s_add_i32 m0, m0, 0x400
	s_add_u32 s28, s28, s32
	s_addc_u32 s29, s29, 0
	global_load_lds_dwordx4 v60, s[28:29]
	s_add_i32 m0, m0, 0x400
	s_add_u32 s28, s28, s32
	s_addc_u32 s29, s29, 0
	global_load_lds_dwordx4 v61, s[28:29]
	s_mov_b64 exec, -1
